# pool_diff: batched-load path also for rows near the sequence start and for the sample rows (all rows now use it)
# speedup vs baseline: 1.0022x; 1.0022x over previous
; __device__ __forceinline__ u32x2 pack4(const f32x4& v) { u32x2 w; w.x = pk2(v[0], v[1]); w.y = pk2(v[2], v[3]); return w; }
; template <int W>
; __device__ __forceinline__ void pool_diff_store(bf16_t* D, int m, int c0, const f32x4 (&v)[W]) {
;     int cnt = W; if (m < MPT) { const int s = m & (SEQ - 1); cnt = (s + 1 < W) ? s + 1 : W; }
;     f32x4 sum = v[0];
; #pragma unroll
;     for (int j = 1; j < W; ++j) sum += v[j];
;     *(u32x2*)(D + (size_t)m * 1024 + c0) = pack4(sum * (1.f / (float)cnt) - v[0]);
; }
; __device__ __forceinline__ void s2_pool_diff(Frame& F, int l) {
;     ...
;     for (int m = F.gw; m < MROWS; m += F.ngw) {
;         f32x4 v2[2], v4[4], v8[8], v16[16];
;         pool_diff_load<2>(P, spool, m, c0, v2); pool_diff_load<4>(P, spool, m, 256 + c0, v4); pool_diff_load<8>(P, spool, m, 512 + c0, v8); pool_diff_load<16>(P, spool, m, 768 + c0, v16);
;         pool_diff_store<2>(D, m, c0, v2); pool_diff_store<4>(D, m, 256 + c0, v4); pool_diff_store<8>(D, m, 512 + c0, v8); pool_diff_store<16>(D, m, 768 + c0, v16);
.LBB0_427:
	v_mov_b32_e32 v2, v0
	v_readlane_b32 s24, v252, 0
	v_readfirstlane_b32 s8, v2
	s_ashr_i32 s4, s8, 6
	s_add_i32 s44, s4, s81
	v_readlane_b32 s25, v252, 1
	v_readlane_b32 s26, v252, 2
	v_readlane_b32 s27, v252, 3
	s_mov_b64 s[22:23], s[26:27]
	s_mov_b64 s[16:17], s[24:25]
	s_cmpk_gt_i32 s44, 0x201f
	s_cbranch_scc1 .LBB0_543
	s_load_dwordx2 s[16:17], s[0:1], 0x28
	v_lshlrev_b32_e32 v3, 2, v2
	v_and_b32_e32 v4, 0xfc, v3
	v_lshlrev_b32_e32 v98, 1, v4
	v_lshlrev_b32_e32 v6, 2, v4
	s_waitcnt lgkmcnt(0)
	s_add_u32 s46, s16, s50
	s_addc_u32 s47, s17, s51
	s_add_u32 s24, s22, 0xc800000
	s_addc_u32 s25, s23, 0
	v_mov_b32_e32 v7, v99
	s_bfe_u32 s8, s8, 0x20006
	v_lshl_add_u64 v[128:129], s[46:47], 0, v[6:7]
	s_add_i32 s14, s8, 0x1ff1
	v_or_b32_e32 v6, 0x200, v98
	s_cmp_lg_u32 s8, 0
	v_lshl_add_u64 v[130:131], s[24:25], 0, v[6:7]
	v_or_b32_e32 v6, 0x400, v98
	s_cselect_b64 s[56:57], -1, 0
	s_add_i32 s16, s8, 13
	v_lshl_add_u64 v[132:133], s[24:25], 0, v[6:7]
	v_or_b32_e32 v6, 0x600, v98
	v_lshl_add_u64 v[126:127], s[24:25], 0, v[98:99]
	s_cmp_lt_u32 s8, 2
	s_waitcnt vmcnt(0)
	v_lshl_add_u64 v[134:135], s[24:25], 0, v[6:7]
	v_lshl_add_u64 v[6:7], s[22:23], 0, v[98:99]
	s_mov_b64 s[24:25], 0x1ae00000
	s_cselect_b64 s[58:59], -1, 0
	s_cmp_lg_u32 s8, 3
	v_lshl_add_u64 v[136:137], v[6:7], 0, s[24:25]
	v_readlane_b32 s24, v254, 49
	s_cselect_b64 s[60:61], -1, 0
	s_or_b32 s17, s8, 12
	s_add_i32 s26, s8, 11
	s_add_i32 s27, s8, 10
	s_add_i32 s28, s8, 9
	s_or_b32 s29, s8, 8
	s_add_i32 s30, s8, 7
	s_add_i32 s31, s8, 6
	s_add_i32 s34, s8, 5
	s_or_b32 s35, s8, 4
	s_add_i32 s36, s8, 3
	s_add_i32 s37, s8, 2
	s_add_i32 s66, s8, 1
	s_add_i32 s67, s24, s4
	s_ashr_i32 s45, s44, 31
	s_mul_i32 s24, s44, 0x6e00
	s_mul_hi_i32 s4, s44, 0x6e00
	v_and_b32_e32 v2, 63, v2
	s_add_u32 s22, s22, s24
	v_lshlrev_b32_e32 v98, 3, v2
	s_addc_u32 s23, s23, s4
	v_lshl_add_u64 v[2:3], s[22:23], 0, v[98:99]
	s_mov_b64 s[22:23], 0xc800600
	v_lshl_add_u64 v[138:139], v[2:3], 0, s[22:23]
	v_lshlrev_b32_e32 v98, 2, v4
	s_branch .LBB0_431
.LBB0_430:
	s_cmp_eq_u32 s64, 0
	s_cselect_b32 s4, 1.0, 0.5
	v_mov_b32_e32 v125, s4
	s_min_u32 s4, s64, 3
	v_pk_add_f32 v[4:5], v[4:5], v[8:9]
	v_pk_add_f32 v[2:3], v[2:3], v[6:7]
	v_cndmask_b32_e64 v140, 0.5, v125, s[40:41]
	v_xor_b32_e32 v9, 0x80000000, v9
	v_xor_b32_e32 v8, 0x80000000, v8
	s_add_i32 s4, s4, 1
	v_pk_fma_f32 v[4:5], v[4:5], v[140:141], v[8:9] op_sel_hi:[1,0,1]
	v_pk_fma_f32 v[2:3], v[2:3], v[140:141], v[6:7] op_sel_hi:[1,0,1] neg_lo:[0,0,1] neg_hi:[0,0,1]
	s_lshl_b64 s[22:23], s[22:23], 11
	v_cvt_f32_ubyte0_e32 v8, s4
	v_cvt_pk_bf16_f32 v2, v2, v3
	v_cvt_pk_bf16_f32 v3, v4, v5
	v_lshl_add_u64 v[4:5], v[136:137], 0, s[22:23]
	v_div_scale_f32 v9, s[22:23], v8, v8, 1.0
	v_pk_add_f32 v[6:7], v[10:11], v[22:23]
	v_rcp_f32_e32 v10, v9
	global_store_dwordx2 v[4:5], v[2:3], off
	v_pk_add_f32 v[2:3], v[12:13], v[24:25]
	v_pk_add_f32 v[6:7], v[14:15], v[6:7]
	v_fma_f32 v11, -v9, v10, 1.0
	v_fmac_f32_e32 v10, v11, v10
	v_div_scale_f32 v11, vcc, 1.0, v8, 1.0
	v_mul_f32_e32 v12, v11, v10
	v_fma_f32 v13, -v9, v12, v11
	v_fmac_f32_e32 v12, v13, v10
	v_fma_f32 v9, -v9, v12, v11
	v_div_fmas_f32 v9, v9, v10, v12
	v_pk_add_f32 v[2:3], v[16:17], v[2:3]
	v_div_fixup_f32 v8, v9, v8, 1.0
	v_mov_b32_e32 v9, 0x3e800000
	s_min_u32 s4, s64, 7
	v_pk_add_f32 v[6:7], v[18:19], v[6:7]
	v_pk_add_f32 v[2:3], v[20:21], v[2:3]
	v_cndmask_b32_e64 v8, v9, v8, s[40:41]
	v_xor_b32_e32 v11, 0x80000000, v25
	v_xor_b32_e32 v10, 0x80000000, v24
	s_add_i32 s4, s4, 1
	v_pk_fma_f32 v[2:3], v[2:3], v[8:9], v[10:11] op_sel_hi:[1,0,1]
	v_pk_fma_f32 v[6:7], v[6:7], v[8:9], v[22:23] op_sel_hi:[1,0,1] neg_lo:[0,0,1] neg_hi:[0,0,1]
	v_cvt_f32_ubyte0_e32 v8, s4
	v_div_scale_f32 v9, s[22:23], v8, v8, 1.0
	v_rcp_f32_e32 v10, v9
	v_cvt_pk_bf16_f32 v6, v6, v7
	v_cvt_pk_bf16_f32 v7, v2, v3
	global_store_dwordx2 v[4:5], v[6:7], off offset:512
	v_fma_f32 v11, -v9, v10, 1.0
	v_fmac_f32_e32 v10, v11, v10
	v_div_scale_f32 v11, vcc, 1.0, v8, 1.0
	v_pk_add_f32 v[2:3], v[28:29], v[56:57]
	v_pk_add_f32 v[6:7], v[26:27], v[54:55]
	v_mul_f32_e32 v12, v11, v10
	v_pk_add_f32 v[2:3], v[32:33], v[2:3]
	v_pk_add_f32 v[6:7], v[30:31], v[6:7]
	v_fma_f32 v13, -v9, v12, v11
	v_pk_add_f32 v[2:3], v[36:37], v[2:3]
	v_pk_add_f32 v[6:7], v[34:35], v[6:7]
	v_fmac_f32_e32 v12, v13, v10
	s_waitcnt vmcnt(5)
	v_pk_add_f32 v[2:3], v[40:41], v[2:3]
	v_pk_add_f32 v[6:7], v[38:39], v[6:7]
	v_fma_f32 v9, -v9, v12, v11
	s_waitcnt vmcnt(4)
	v_pk_add_f32 v[2:3], v[44:45], v[2:3]
	v_pk_add_f32 v[6:7], v[42:43], v[6:7]
	v_div_fmas_f32 v9, v9, v10, v12
	s_waitcnt vmcnt(3)
	v_pk_add_f32 v[2:3], v[48:49], v[2:3]
	v_pk_add_f32 v[6:7], v[46:47], v[6:7]
	v_div_fixup_f32 v8, v9, v8, 1.0
	v_mov_b32_e32 v9, 0x3e000000
	s_waitcnt vmcnt(2)
; __device__ __forceinline__ u32x2 pack4(const f32x4& v) { u32x2 w; w.x = pk2(v[0], v[1]); w.y = pk2(v[2], v[3]); return w; }
; __device__ __forceinline__ f32x4 unpack4(const u32x2& x) { return (f32x4){bf2f(x.x & 0xffffu), __uint_as_float(x.x & 0xffff0000u), bf2f(x.y & 0xffffu), __uint_as_float(x.y & 0xffff0000u)}; }
; template <int W>
; __device__ __forceinline__ void pool_diff_load(const bf16_t* P, const float* spool, int m, int c0, f32x4 (&v)[W]) {
;     if (m < MPT) {
;         const int s = m & (SEQ - 1);
; #pragma unroll
;         for (int j = 0; j < W; ++j) v[j] = (j <= s) ? unpack4(*(const u32x2*)(P + (size_t)(m - j) * NPROJ + C_PU + c0)) : (f32x4){0.f, 0.f, 0.f, 0.f};
;     } else {
; template <int W>
; __device__ __forceinline__ void pool_diff_store(bf16_t* D, int m, int c0, const f32x4 (&v)[W]) {
;     int cnt = W; if (m < MPT) { const int s = m & (SEQ - 1); cnt = (s + 1 < W) ? s + 1 : W; }
;     f32x4 sum = v[0];
; #pragma unroll
;     for (int j = 1; j < W; ++j) sum += v[j];
;     *(u32x2*)(D + (size_t)m * 1024 + c0) = pack4(sum * (1.f / (float)cnt) - v[0]);
; }
	v_pk_add_f32 v[6:7], v[50:51], v[6:7]
	v_pk_add_f32 v[2:3], v[52:53], v[2:3]
	v_cndmask_b32_e64 v8, v9, v8, s[40:41]
	v_xor_b32_e32 v11, 0x80000000, v57
	v_xor_b32_e32 v10, 0x80000000, v56
	v_pk_fma_f32 v[2:3], v[2:3], v[8:9], v[10:11] op_sel_hi:[1,0,1]
	v_pk_fma_f32 v[6:7], v[6:7], v[8:9], v[54:55] op_sel_hi:[1,0,1] neg_lo:[0,0,1] neg_hi:[0,0,1]
	s_min_u32 s4, s64, 15
	v_cvt_pk_bf16_f32 v6, v6, v7
	v_cvt_pk_bf16_f32 v7, v2, v3
	s_add_i32 s4, s4, 1
	global_store_dwordx2 v[4:5], v[6:7], off offset:1024
	v_pk_add_f32 v[2:3], v[60:61], v[122:123]
	v_pk_add_f32 v[6:7], v[58:59], v[120:121]
	v_cvt_f32_ubyte0_e32 v8, s4
	v_pk_add_f32 v[2:3], v[64:65], v[2:3]
	v_pk_add_f32 v[6:7], v[62:63], v[6:7]
	v_div_scale_f32 v9, s[22:23], v8, v8, 1.0
	v_pk_add_f32 v[2:3], v[68:69], v[2:3]
	v_pk_add_f32 v[6:7], v[66:67], v[6:7]
	v_rcp_f32_e32 v10, v9
	v_pk_add_f32 v[2:3], v[72:73], v[2:3]
	v_pk_add_f32 v[6:7], v[70:71], v[6:7]
	v_pk_add_f32 v[2:3], v[76:77], v[2:3]
	v_pk_add_f32 v[6:7], v[74:75], v[6:7]
	v_pk_add_f32 v[2:3], v[80:81], v[2:3]
	v_pk_add_f32 v[6:7], v[78:79], v[6:7]
	v_pk_add_f32 v[2:3], v[84:85], v[2:3]
	v_pk_add_f32 v[6:7], v[82:83], v[6:7]
	v_fma_f32 v11, -v9, v10, 1.0
	v_pk_add_f32 v[2:3], v[88:89], v[2:3]
	v_pk_add_f32 v[6:7], v[86:87], v[6:7]
	v_fmac_f32_e32 v10, v11, v10
	v_div_scale_f32 v11, vcc, 1.0, v8, 1.0
	v_pk_add_f32 v[2:3], v[92:93], v[2:3]
	v_pk_add_f32 v[6:7], v[90:91], v[6:7]
	v_mul_f32_e32 v12, v11, v10
	v_pk_add_f32 v[2:3], v[96:97], v[2:3]
	v_pk_add_f32 v[6:7], v[94:95], v[6:7]
	v_fma_f32 v13, -v9, v12, v11
	v_pk_add_f32 v[2:3], v[102:103], v[2:3]
	v_pk_add_f32 v[6:7], v[100:101], v[6:7]
	v_fmac_f32_e32 v12, v13, v10
	v_pk_add_f32 v[2:3], v[106:107], v[2:3]
	v_pk_add_f32 v[6:7], v[104:105], v[6:7]
	v_fma_f32 v9, -v9, v12, v11
	v_pk_add_f32 v[2:3], v[110:111], v[2:3]
	v_pk_add_f32 v[6:7], v[108:109], v[6:7]
	v_div_fmas_f32 v9, v9, v10, v12
	s_add_i32 s67, s67, s88
	v_pk_add_f32 v[2:3], v[114:115], v[2:3]
	v_pk_add_f32 v[6:7], v[112:113], v[6:7]
	v_div_fixup_f32 v8, v9, v8, 1.0
	v_mov_b32_e32 v9, 0x3d800000
	s_add_i32 s4, s67, 0x2000
	v_pk_add_f32 v[6:7], v[116:117], v[6:7]
	v_pk_add_f32 v[2:3], v[118:119], v[2:3]
	v_cndmask_b32_e64 v8, v9, v8, s[40:41]
	v_xor_b32_e32 v11, 0x80000000, v123
	v_xor_b32_e32 v10, 0x80000000, v122
	s_add_u32 s44, s44, s88
	v_readlane_b32 s22, v252, 10
	v_pk_fma_f32 v[2:3], v[8:9], v[2:3], v[10:11] op_sel_hi:[0,1,1]
	v_pk_fma_f32 v[6:7], v[8:9], v[6:7], v[120:121] op_sel_hi:[0,1,1] neg_lo:[0,0,1] neg_hi:[0,0,1]
	s_addc_u32 s45, s45, s89
	v_readlane_b32 s23, v252, 11
	v_cvt_pk_bf16_f32 v6, v6, v7
	v_cvt_pk_bf16_f32 v7, v2, v3
	s_cmpk_lt_i32 s4, 0x2020
	v_lshl_add_u64 v[138:139], v[138:139], 0, s[22:23]
	global_store_dwordx2 v[4:5], v[6:7], off offset:1536
	s_cbranch_scc0 .LBB0_542
.LBB0_431:
	s_add_i32 s4, s67, 0x2000
	s_cmpk_lt_i32 s4, 0x2000
	s_cselect_b64 s[40:41], -1, 0
	s_cmpk_gt_i32 s4, 0x1fff
	s_cselect_b64 s[64:65], -1, 0
	s_cbranch_scc1 .Lpd_sample
	s_mov_b32 s22, 0xffff9200
	s_mov_b32 s23, -1
	v_mov_b64_e32 v[142:143], v[138:139]
	global_load_dwordx2 v[144:145], v[142:143], off offset:-1536
	global_load_dwordx2 v[146:147], v[142:143], off offset:-1024
	global_load_dwordx2 v[148:149], v[142:143], off offset:-512
	global_load_dwordx2 v[150:151], v[142:143], off
	v_lshl_add_u64 v[142:143], v[142:143], 0, s[22:23]
	global_load_dwordx2 v[152:153], v[142:143], off offset:-1536
	global_load_dwordx2 v[154:155], v[142:143], off offset:-1024
	global_load_dwordx2 v[156:157], v[142:143], off offset:-512
	global_load_dwordx2 v[158:159], v[142:143], off
	v_lshl_add_u64 v[142:143], v[142:143], 0, s[22:23]
	global_load_dwordx2 v[160:161], v[142:143], off offset:-1024
	global_load_dwordx2 v[162:163], v[142:143], off offset:-512
	global_load_dwordx2 v[164:165], v[142:143], off
	v_lshl_add_u64 v[142:143], v[142:143], 0, s[22:23]
	global_load_dwordx2 v[166:167], v[142:143], off offset:-1024
	global_load_dwordx2 v[168:169], v[142:143], off offset:-512
	global_load_dwordx2 v[170:171], v[142:143], off
	v_lshl_add_u64 v[142:143], v[142:143], 0, s[22:23]
	global_load_dwordx2 v[172:173], v[142:143], off offset:-512
	global_load_dwordx2 v[174:175], v[142:143], off
	v_lshl_add_u64 v[142:143], v[142:143], 0, s[22:23]
	global_load_dwordx2 v[176:177], v[142:143], off offset:-512
	global_load_dwordx2 v[178:179], v[142:143], off
	v_lshl_add_u64 v[142:143], v[142:143], 0, s[22:23]
	global_load_dwordx2 v[180:181], v[142:143], off offset:-512
	global_load_dwordx2 v[182:183], v[142:143], off
	v_lshl_add_u64 v[142:143], v[142:143], 0, s[22:23]
	global_load_dwordx2 v[184:185], v[142:143], off offset:-512
	global_load_dwordx2 v[186:187], v[142:143], off
	v_lshl_add_u64 v[142:143], v[142:143], 0, s[22:23]
	global_load_dwordx2 v[188:189], v[142:143], off
	v_lshl_add_u64 v[142:143], v[142:143], 0, s[22:23]
	global_load_dwordx2 v[190:191], v[142:143], off
	v_lshl_add_u64 v[142:143], v[142:143], 0, s[22:23]
	global_load_dwordx2 v[192:193], v[142:143], off
	v_lshl_add_u64 v[142:143], v[142:143], 0, s[22:23]
	global_load_dwordx2 v[194:195], v[142:143], off
	v_lshl_add_u64 v[142:143], v[142:143], 0, s[22:23]
	global_load_dwordx2 v[206:207], v[142:143], off
	v_lshl_add_u64 v[142:143], v[142:143], 0, s[22:23]
	global_load_dwordx2 v[208:209], v[142:143], off
	v_lshl_add_u64 v[142:143], v[142:143], 0, s[22:23]
	global_load_dwordx2 v[210:211], v[142:143], off
	v_lshl_add_u64 v[142:143], v[142:143], 0, s[22:23]
	global_load_dwordx2 v[212:213], v[142:143], off
	s_waitcnt vmcnt(26)
; __device__ __forceinline__ f32x4 unpack4(const u32x2& x) { return (f32x4){bf2f(x.x & 0xffffu), __uint_as_float(x.x & 0xffff0000u), bf2f(x.y & 0xffffu), __uint_as_float(x.y & 0xffff0000u)}; }
; template <int W>
; __device__ __forceinline__ void pool_diff_load(const bf16_t* P, const float* spool, int m, int c0, f32x4 (&v)[W]) {
;     if (m < MPT) {
;         const int s = m & (SEQ - 1);
; #pragma unroll
;         for (int j = 0; j < W; ++j) v[j] = (j <= s) ? unpack4(*(const u32x2*)(P + (size_t)(m - j) * NPROJ + C_PU + c0)) : (f32x4){0.f, 0.f, 0.f, 0.f};
;     } else {
	v_lshlrev_b32_e32 v6, 16, v144
	v_and_b32_e32 v7, 0xffff0000, v144
	v_lshlrev_b32_e32 v8, 16, v145
	v_and_b32_e32 v9, 0xffff0000, v145
	v_lshlrev_b32_e32 v22, 16, v146
	v_and_b32_e32 v23, 0xffff0000, v146
	v_lshlrev_b32_e32 v24, 16, v147
	v_and_b32_e32 v25, 0xffff0000, v147
	v_lshlrev_b32_e32 v54, 16, v148
	v_and_b32_e32 v55, 0xffff0000, v148
	v_lshlrev_b32_e32 v56, 16, v149
	v_and_b32_e32 v57, 0xffff0000, v149
	v_lshlrev_b32_e32 v120, 16, v150
	v_and_b32_e32 v121, 0xffff0000, v150
	v_lshlrev_b32_e32 v122, 16, v151
	v_and_b32_e32 v123, 0xffff0000, v151
	s_waitcnt vmcnt(22)
	v_lshlrev_b32_e32 v2, 16, v152
	v_and_b32_e32 v3, 0xffff0000, v152
	v_lshlrev_b32_e32 v4, 16, v153
	v_and_b32_e32 v5, 0xffff0000, v153
	v_lshlrev_b32_e32 v10, 16, v154
	v_and_b32_e32 v11, 0xffff0000, v154
	v_lshlrev_b32_e32 v12, 16, v155
	v_and_b32_e32 v13, 0xffff0000, v155
	v_lshlrev_b32_e32 v26, 16, v156
	v_and_b32_e32 v27, 0xffff0000, v156
	v_lshlrev_b32_e32 v28, 16, v157
	v_and_b32_e32 v29, 0xffff0000, v157
	v_lshlrev_b32_e32 v58, 16, v158
	v_and_b32_e32 v59, 0xffff0000, v158
	v_lshlrev_b32_e32 v60, 16, v159
	v_and_b32_e32 v61, 0xffff0000, v159
	s_waitcnt vmcnt(18)
	v_lshlrev_b32_e32 v14, 16, v160
	v_and_b32_e32 v15, 0xffff0000, v160
	v_lshlrev_b32_e32 v16, 16, v161
	v_and_b32_e32 v17, 0xffff0000, v161
	v_lshlrev_b32_e32 v30, 16, v162
	v_and_b32_e32 v31, 0xffff0000, v162
	v_lshlrev_b32_e32 v32, 16, v163
	v_and_b32_e32 v33, 0xffff0000, v163
	v_lshlrev_b32_e32 v62, 16, v164
	v_and_b32_e32 v63, 0xffff0000, v164
	v_lshlrev_b32_e32 v64, 16, v165
	v_and_b32_e32 v65, 0xffff0000, v165
	v_lshlrev_b32_e32 v18, 16, v166
	v_and_b32_e32 v19, 0xffff0000, v166
	v_lshlrev_b32_e32 v20, 16, v167
	v_and_b32_e32 v21, 0xffff0000, v167
	s_waitcnt vmcnt(14)
	v_lshlrev_b32_e32 v34, 16, v168
	v_and_b32_e32 v35, 0xffff0000, v168
	v_lshlrev_b32_e32 v36, 16, v169
	v_and_b32_e32 v37, 0xffff0000, v169
	v_lshlrev_b32_e32 v66, 16, v170
	v_and_b32_e32 v67, 0xffff0000, v170
	v_lshlrev_b32_e32 v68, 16, v171
	v_and_b32_e32 v69, 0xffff0000, v171
	v_lshlrev_b32_e32 v38, 16, v172
	v_and_b32_e32 v39, 0xffff0000, v172
	v_lshlrev_b32_e32 v40, 16, v173
	v_and_b32_e32 v41, 0xffff0000, v173
	v_lshlrev_b32_e32 v70, 16, v174
	v_and_b32_e32 v71, 0xffff0000, v174
	v_lshlrev_b32_e32 v72, 16, v175
	v_and_b32_e32 v73, 0xffff0000, v175
	s_waitcnt vmcnt(10)
	v_lshlrev_b32_e32 v42, 16, v176
	v_and_b32_e32 v43, 0xffff0000, v176
	v_lshlrev_b32_e32 v44, 16, v177
	v_and_b32_e32 v45, 0xffff0000, v177
	v_lshlrev_b32_e32 v74, 16, v178
	v_and_b32_e32 v75, 0xffff0000, v178
	v_lshlrev_b32_e32 v76, 16, v179
	v_and_b32_e32 v77, 0xffff0000, v179
	v_lshlrev_b32_e32 v46, 16, v180
	v_and_b32_e32 v47, 0xffff0000, v180
	v_lshlrev_b32_e32 v48, 16, v181
	v_and_b32_e32 v49, 0xffff0000, v181
	v_lshlrev_b32_e32 v78, 16, v182
	v_and_b32_e32 v79, 0xffff0000, v182
	v_lshlrev_b32_e32 v80, 16, v183
	v_and_b32_e32 v81, 0xffff0000, v183
	s_waitcnt vmcnt(6)
	v_lshlrev_b32_e32 v50, 16, v184
	v_and_b32_e32 v51, 0xffff0000, v184
	v_lshlrev_b32_e32 v52, 16, v185
	v_and_b32_e32 v53, 0xffff0000, v185
	v_lshlrev_b32_e32 v82, 16, v186
	v_and_b32_e32 v83, 0xffff0000, v186
	v_lshlrev_b32_e32 v84, 16, v187
	v_and_b32_e32 v85, 0xffff0000, v187
	v_lshlrev_b32_e32 v86, 16, v188
	v_and_b32_e32 v87, 0xffff0000, v188
	v_lshlrev_b32_e32 v88, 16, v189
	v_and_b32_e32 v89, 0xffff0000, v189
	v_lshlrev_b32_e32 v90, 16, v190
	v_and_b32_e32 v91, 0xffff0000, v190
	v_lshlrev_b32_e32 v92, 16, v191
	v_and_b32_e32 v93, 0xffff0000, v191
	s_waitcnt vmcnt(2)
	v_lshlrev_b32_e32 v94, 16, v192
	v_and_b32_e32 v95, 0xffff0000, v192
	v_lshlrev_b32_e32 v96, 16, v193
	v_and_b32_e32 v97, 0xffff0000, v193
	v_lshlrev_b32_e32 v100, 16, v194
	v_and_b32_e32 v101, 0xffff0000, v194
	v_lshlrev_b32_e32 v102, 16, v195
	v_and_b32_e32 v103, 0xffff0000, v195
	v_lshlrev_b32_e32 v104, 16, v206
	v_and_b32_e32 v105, 0xffff0000, v206
	v_lshlrev_b32_e32 v106, 16, v207
	v_and_b32_e32 v107, 0xffff0000, v207
	v_lshlrev_b32_e32 v108, 16, v208
	v_and_b32_e32 v109, 0xffff0000, v208
	v_lshlrev_b32_e32 v110, 16, v209
	v_and_b32_e32 v111, 0xffff0000, v209
	s_waitcnt vmcnt(0)
	v_lshlrev_b32_e32 v112, 16, v210
	v_and_b32_e32 v113, 0xffff0000, v210
	v_lshlrev_b32_e32 v114, 16, v211
	v_and_b32_e32 v115, 0xffff0000, v211
	v_lshlrev_b32_e32 v116, 16, v212
	v_and_b32_e32 v117, 0xffff0000, v212
	v_lshlrev_b32_e32 v118, 16, v213
	v_and_b32_e32 v119, 0xffff0000, v213
	s_and_b32 s64, s4, 0xfff
	s_cmp_gt_u32 s64, 14
	s_cbranch_scc1 .Lpd_join
	v_mov_b32_e32 v116, 0
	v_mov_b32_e32 v117, 0
	v_mov_b32_e32 v118, 0
	v_mov_b32_e32 v119, 0
	s_cmp_ge_u32 s64, 14
	s_cbranch_scc1 .Lpd_join
	v_mov_b32_e32 v112, 0
	v_mov_b32_e32 v113, 0
	v_mov_b32_e32 v114, 0
	v_mov_b32_e32 v115, 0
	s_cmp_ge_u32 s64, 13
	s_cbranch_scc1 .Lpd_join
	v_mov_b32_e32 v108, 0
	v_mov_b32_e32 v109, 0
	v_mov_b32_e32 v110, 0
	v_mov_b32_e32 v111, 0
	s_cmp_ge_u32 s64, 12
	s_cbranch_scc1 .Lpd_join
	v_mov_b32_e32 v104, 0
	v_mov_b32_e32 v105, 0
	v_mov_b32_e32 v106, 0
	v_mov_b32_e32 v107, 0
	s_cmp_ge_u32 s64, 11
	s_cbranch_scc1 .Lpd_join
	v_mov_b32_e32 v100, 0
	v_mov_b32_e32 v101, 0
	v_mov_b32_e32 v102, 0
	v_mov_b32_e32 v103, 0
	s_cmp_ge_u32 s64, 10
	s_cbranch_scc1 .Lpd_join
	v_mov_b32_e32 v94, 0
	v_mov_b32_e32 v95, 0
	v_mov_b32_e32 v96, 0
	v_mov_b32_e32 v97, 0
	s_cmp_ge_u32 s64, 9
	s_cbranch_scc1 .Lpd_join
	v_mov_b32_e32 v90, 0
	v_mov_b32_e32 v91, 0
	v_mov_b32_e32 v92, 0
	v_mov_b32_e32 v93, 0
	s_cmp_ge_u32 s64, 8
	s_cbranch_scc1 .Lpd_join
	v_mov_b32_e32 v86, 0
	v_mov_b32_e32 v87, 0
	v_mov_b32_e32 v88, 0
	v_mov_b32_e32 v89, 0
	s_cmp_ge_u32 s64, 7
	s_cbranch_scc1 .Lpd_join
; __device__ __forceinline__ f32x4 unpack4(const u32x2& x) { return (f32x4){bf2f(x.x & 0xffffu), __uint_as_float(x.x & 0xffff0000u), bf2f(x.y & 0xffffu), __uint_as_float(x.y & 0xffff0000u)}; }
; template <int W>
; __device__ __forceinline__ void pool_diff_load(const bf16_t* P, const float* spool, int m, int c0, f32x4 (&v)[W]) {
;     if (m < MPT) {
;         const int s = m & (SEQ - 1);
; #pragma unroll
;         for (int j = 0; j < W; ++j) v[j] = (j <= s) ? unpack4(*(const u32x2*)(P + (size_t)(m - j) * NPROJ + C_PU + c0)) : (f32x4){0.f, 0.f, 0.f, 0.f};
;     } else {
;         const int b = (m - MPT) >> 2, i = (m - MPT) & 3;
; #pragma unroll
;         for (int j = 0; j < W; ++j) { const int idx = 15 + i - j;
;             v[j] = (idx >= 15) ? unpack4(*(const u32x2*)(P + (size_t)(MPT + b * 4 + idx - 15) * NPROJ + C_PU + c0)) : *(const f32x4*)(spool + ((size_t)b * 15 + idx) * 1024 + c0); }
;     }
	v_mov_b32_e32 v50, 0
	v_mov_b32_e32 v51, 0
	v_mov_b32_e32 v52, 0
	v_mov_b32_e32 v53, 0
	v_mov_b32_e32 v82, 0
	v_mov_b32_e32 v83, 0
	v_mov_b32_e32 v84, 0
	v_mov_b32_e32 v85, 0
	s_cmp_ge_u32 s64, 6
	s_cbranch_scc1 .Lpd_join
	v_mov_b32_e32 v46, 0
	v_mov_b32_e32 v47, 0
	v_mov_b32_e32 v48, 0
	v_mov_b32_e32 v49, 0
	v_mov_b32_e32 v78, 0
	v_mov_b32_e32 v79, 0
	v_mov_b32_e32 v80, 0
	v_mov_b32_e32 v81, 0
	s_cmp_ge_u32 s64, 5
	s_cbranch_scc1 .Lpd_join
	v_mov_b32_e32 v42, 0
	v_mov_b32_e32 v43, 0
	v_mov_b32_e32 v44, 0
	v_mov_b32_e32 v45, 0
	v_mov_b32_e32 v74, 0
	v_mov_b32_e32 v75, 0
	v_mov_b32_e32 v76, 0
	v_mov_b32_e32 v77, 0
	s_cmp_ge_u32 s64, 4
	s_cbranch_scc1 .Lpd_join
	v_mov_b32_e32 v38, 0
	v_mov_b32_e32 v39, 0
	v_mov_b32_e32 v40, 0
	v_mov_b32_e32 v41, 0
	v_mov_b32_e32 v70, 0
	v_mov_b32_e32 v71, 0
	v_mov_b32_e32 v72, 0
	v_mov_b32_e32 v73, 0
	s_cmp_ge_u32 s64, 3
	s_cbranch_scc1 .Lpd_join
	v_mov_b32_e32 v18, 0
	v_mov_b32_e32 v19, 0
	v_mov_b32_e32 v20, 0
	v_mov_b32_e32 v21, 0
	v_mov_b32_e32 v34, 0
	v_mov_b32_e32 v35, 0
	v_mov_b32_e32 v36, 0
	v_mov_b32_e32 v37, 0
	v_mov_b32_e32 v66, 0
	v_mov_b32_e32 v67, 0
	v_mov_b32_e32 v68, 0
	v_mov_b32_e32 v69, 0
	s_cmp_ge_u32 s64, 2
	s_cbranch_scc1 .Lpd_join
	v_mov_b32_e32 v14, 0
	v_mov_b32_e32 v15, 0
	v_mov_b32_e32 v16, 0
	v_mov_b32_e32 v17, 0
	v_mov_b32_e32 v30, 0
	v_mov_b32_e32 v31, 0
	v_mov_b32_e32 v32, 0
	v_mov_b32_e32 v33, 0
	v_mov_b32_e32 v62, 0
	v_mov_b32_e32 v63, 0
	v_mov_b32_e32 v64, 0
	v_mov_b32_e32 v65, 0
	s_cmp_ge_u32 s64, 1
	s_cbranch_scc1 .Lpd_join
	v_mov_b32_e32 v2, 0
	v_mov_b32_e32 v3, 0
	v_mov_b32_e32 v4, 0
	v_mov_b32_e32 v5, 0
	v_mov_b32_e32 v10, 0
	v_mov_b32_e32 v11, 0
	v_mov_b32_e32 v12, 0
	v_mov_b32_e32 v13, 0
	v_mov_b32_e32 v26, 0
	v_mov_b32_e32 v27, 0
	v_mov_b32_e32 v28, 0
	v_mov_b32_e32 v29, 0
	v_mov_b32_e32 v58, 0
	v_mov_b32_e32 v59, 0
	v_mov_b32_e32 v60, 0
	v_mov_b32_e32 v61, 0
.Lpd_join:
	s_mov_b64 s[22:23], s[44:45]
	s_branch .LBB0_430
.Lpd_sample:
	s_lshr_b32 s22, s67, 2
	s_mul_i32 s22, s22, 15
	s_add_i32 s22, s22, s8
	s_add_i32 s22, s22, 15
	s_lshl_b32 s22, s22, 12
	s_mov_b32 s23, 0
	v_lshl_add_u64 v[140:141], v[128:129], 0, s[22:23]
	v_mov_b64_e32 v[142:143], v[138:139]
	s_mov_b32 s22, 0xffff9200
	s_mov_b32 s23, -1
	s_cmp_ge_u32 s8, 0
	s_cbranch_scc0 .Lpd_sp0
	global_load_dwordx2 v[144:145], v[142:143], off offset:-1536
	global_load_dwordx2 v[146:147], v[142:143], off offset:-1024
	global_load_dwordx2 v[148:149], v[142:143], off offset:-512
	global_load_dwordx2 v[150:151], v[142:143], off
	s_branch .Lpd_nx0
.Lpd_sp0:
	global_load_dwordx4 v[6:9], v[140:141], off
	global_load_dwordx4 v[22:25], v[140:141], off offset:1024
	global_load_dwordx4 v[54:57], v[140:141], off offset:2048
	global_load_dwordx4 v[120:123], v[140:141], off offset:3072
.Lpd_nx0:
	v_lshl_add_u64 v[142:143], v[142:143], 0, s[22:23]
	v_add_co_u32_e32 v140, vcc, 0xfffff000, v140
	s_nop 1
	v_addc_co_u32_e32 v141, vcc, -1, v141, vcc
	s_cmp_ge_u32 s8, 1
	s_cbranch_scc0 .Lpd_sp1
	global_load_dwordx2 v[152:153], v[142:143], off offset:-1536
	global_load_dwordx2 v[154:155], v[142:143], off offset:-1024
	global_load_dwordx2 v[156:157], v[142:143], off offset:-512
	global_load_dwordx2 v[158:159], v[142:143], off
	s_branch .Lpd_nx1
.Lpd_sp1:
	global_load_dwordx4 v[2:5], v[140:141], off
	global_load_dwordx4 v[10:13], v[140:141], off offset:1024
	global_load_dwordx4 v[26:29], v[140:141], off offset:2048
	global_load_dwordx4 v[58:61], v[140:141], off offset:3072
.Lpd_nx1:
	v_lshl_add_u64 v[142:143], v[142:143], 0, s[22:23]
	v_add_co_u32_e32 v140, vcc, 0xfffff000, v140
	s_nop 1
	v_addc_co_u32_e32 v141, vcc, -1, v141, vcc
	s_cmp_ge_u32 s8, 2
	s_cbranch_scc0 .Lpd_sp2
	global_load_dwordx2 v[160:161], v[142:143], off offset:-1024
	global_load_dwordx2 v[162:163], v[142:143], off offset:-512
	global_load_dwordx2 v[164:165], v[142:143], off
	s_branch .Lpd_nx2
.Lpd_sp2:
	global_load_dwordx4 v[14:17], v[140:141], off offset:1024
	global_load_dwordx4 v[30:33], v[140:141], off offset:2048
	global_load_dwordx4 v[62:65], v[140:141], off offset:3072
.Lpd_nx2:
	v_lshl_add_u64 v[142:143], v[142:143], 0, s[22:23]
	v_add_co_u32_e32 v140, vcc, 0xfffff000, v140
	s_nop 1
	v_addc_co_u32_e32 v141, vcc, -1, v141, vcc
	s_cmp_ge_u32 s8, 3
	s_cbranch_scc0 .Lpd_sp3
	global_load_dwordx2 v[166:167], v[142:143], off offset:-1024
	global_load_dwordx2 v[168:169], v[142:143], off offset:-512
	global_load_dwordx2 v[170:171], v[142:143], off
	s_branch .Lpd_nx3
.Lpd_sp3:
	global_load_dwordx4 v[18:21], v[140:141], off offset:1024
	global_load_dwordx4 v[34:37], v[140:141], off offset:2048
	global_load_dwordx4 v[66:69], v[140:141], off offset:3072
; __device__ __forceinline__ f32x4 unpack4(const u32x2& x) { return (f32x4){bf2f(x.x & 0xffffu), __uint_as_float(x.x & 0xffff0000u), bf2f(x.y & 0xffffu), __uint_as_float(x.y & 0xffff0000u)}; }
; template <int W>
; __device__ __forceinline__ void pool_diff_load(const bf16_t* P, const float* spool, int m, int c0, f32x4 (&v)[W]) {
;     ...
;         const int b = (m - MPT) >> 2, i = (m - MPT) & 3;
; #pragma unroll
;         for (int j = 0; j < W; ++j) { const int idx = 15 + i - j;
;             v[j] = (idx >= 15) ? unpack4(*(const u32x2*)(P + (size_t)(MPT + b * 4 + idx - 15) * NPROJ + C_PU + c0)) : *(const f32x4*)(spool + ((size_t)b * 15 + idx) * 1024 + c0); }
;     }
.Lpd_nx3:
	v_add_co_u32_e32 v140, vcc, 0xfffff000, v140
	s_nop 1
	v_addc_co_u32_e32 v141, vcc, -1, v141, vcc
	global_load_dwordx4 v[38:41], v[140:141], off offset:2048
	global_load_dwordx4 v[70:73], v[140:141], off offset:3072
	v_add_co_u32_e32 v140, vcc, 0xfffff000, v140
	s_nop 1
	v_addc_co_u32_e32 v141, vcc, -1, v141, vcc
	global_load_dwordx4 v[42:45], v[140:141], off offset:2048
	global_load_dwordx4 v[74:77], v[140:141], off offset:3072
	v_add_co_u32_e32 v140, vcc, 0xfffff000, v140
	s_nop 1
	v_addc_co_u32_e32 v141, vcc, -1, v141, vcc
	global_load_dwordx4 v[46:49], v[140:141], off offset:2048
	global_load_dwordx4 v[78:81], v[140:141], off offset:3072
	v_add_co_u32_e32 v140, vcc, 0xfffff000, v140
	s_nop 1
	v_addc_co_u32_e32 v141, vcc, -1, v141, vcc
	global_load_dwordx4 v[50:53], v[140:141], off offset:2048
	global_load_dwordx4 v[82:85], v[140:141], off offset:3072
	v_add_co_u32_e32 v140, vcc, 0xfffff000, v140
	s_nop 1
	v_addc_co_u32_e32 v141, vcc, -1, v141, vcc
	global_load_dwordx4 v[86:89], v[140:141], off offset:3072
	v_add_co_u32_e32 v140, vcc, 0xfffff000, v140
	s_nop 1
	v_addc_co_u32_e32 v141, vcc, -1, v141, vcc
	global_load_dwordx4 v[90:93], v[140:141], off offset:3072
	v_add_co_u32_e32 v140, vcc, 0xfffff000, v140
	s_nop 1
	v_addc_co_u32_e32 v141, vcc, -1, v141, vcc
	global_load_dwordx4 v[94:97], v[140:141], off offset:3072
	v_add_co_u32_e32 v140, vcc, 0xfffff000, v140
	s_nop 1
	v_addc_co_u32_e32 v141, vcc, -1, v141, vcc
	global_load_dwordx4 v[100:103], v[140:141], off offset:3072
	v_add_co_u32_e32 v140, vcc, 0xfffff000, v140
	s_nop 1
	v_addc_co_u32_e32 v141, vcc, -1, v141, vcc
	global_load_dwordx4 v[104:107], v[140:141], off offset:3072
	v_add_co_u32_e32 v140, vcc, 0xfffff000, v140
	s_nop 1
	v_addc_co_u32_e32 v141, vcc, -1, v141, vcc
	global_load_dwordx4 v[108:111], v[140:141], off offset:3072
	v_add_co_u32_e32 v140, vcc, 0xfffff000, v140
	s_nop 1
	v_addc_co_u32_e32 v141, vcc, -1, v141, vcc
	global_load_dwordx4 v[112:115], v[140:141], off offset:3072
	v_add_co_u32_e32 v140, vcc, 0xfffff000, v140
	s_nop 1
	v_addc_co_u32_e32 v141, vcc, -1, v141, vcc
	global_load_dwordx4 v[116:119], v[140:141], off offset:3072
	s_waitcnt vmcnt(0)
	s_cmp_ge_u32 s8, 0
	s_cbranch_scc0 .Lpd_su0
	v_lshlrev_b32_e32 v6, 16, v144
	v_and_b32_e32 v7, 0xffff0000, v144
	v_lshlrev_b32_e32 v8, 16, v145
	v_and_b32_e32 v9, 0xffff0000, v145
	v_lshlrev_b32_e32 v22, 16, v146
	v_and_b32_e32 v23, 0xffff0000, v146
	v_lshlrev_b32_e32 v24, 16, v147
	v_and_b32_e32 v25, 0xffff0000, v147
	v_lshlrev_b32_e32 v54, 16, v148
	v_and_b32_e32 v55, 0xffff0000, v148
	v_lshlrev_b32_e32 v56, 16, v149
	v_and_b32_e32 v57, 0xffff0000, v149
	v_lshlrev_b32_e32 v120, 16, v150
	v_and_b32_e32 v121, 0xffff0000, v150
	v_lshlrev_b32_e32 v122, 16, v151
	v_and_b32_e32 v123, 0xffff0000, v151
.Lpd_su0:
	s_cmp_ge_u32 s8, 1
	s_cbranch_scc0 .Lpd_su1
	v_lshlrev_b32_e32 v2, 16, v152
	v_and_b32_e32 v3, 0xffff0000, v152
	v_lshlrev_b32_e32 v4, 16, v153
	v_and_b32_e32 v5, 0xffff0000, v153
	v_lshlrev_b32_e32 v10, 16, v154
	v_and_b32_e32 v11, 0xffff0000, v154
	v_lshlrev_b32_e32 v12, 16, v155
	v_and_b32_e32 v13, 0xffff0000, v155
	v_lshlrev_b32_e32 v26, 16, v156
	v_and_b32_e32 v27, 0xffff0000, v156
	v_lshlrev_b32_e32 v28, 16, v157
	v_and_b32_e32 v29, 0xffff0000, v157
	v_lshlrev_b32_e32 v58, 16, v158
	v_and_b32_e32 v59, 0xffff0000, v158
	v_lshlrev_b32_e32 v60, 16, v159
	v_and_b32_e32 v61, 0xffff0000, v159
.Lpd_su1:
	s_cmp_ge_u32 s8, 2
	s_cbranch_scc0 .Lpd_su2
	v_lshlrev_b32_e32 v14, 16, v160
	v_and_b32_e32 v15, 0xffff0000, v160
	v_lshlrev_b32_e32 v16, 16, v161
	v_and_b32_e32 v17, 0xffff0000, v161
	v_lshlrev_b32_e32 v30, 16, v162
	v_and_b32_e32 v31, 0xffff0000, v162
	v_lshlrev_b32_e32 v32, 16, v163
	v_and_b32_e32 v33, 0xffff0000, v163
	v_lshlrev_b32_e32 v62, 16, v164
	v_and_b32_e32 v63, 0xffff0000, v164
	v_lshlrev_b32_e32 v64, 16, v165
	v_and_b32_e32 v65, 0xffff0000, v165
.Lpd_su2:
	s_cmp_ge_u32 s8, 3
	s_cbranch_scc0 .Lpd_su3
	v_lshlrev_b32_e32 v18, 16, v166
	v_and_b32_e32 v19, 0xffff0000, v166
	v_lshlrev_b32_e32 v20, 16, v167
	v_and_b32_e32 v21, 0xffff0000, v167
	v_lshlrev_b32_e32 v34, 16, v168
	v_and_b32_e32 v35, 0xffff0000, v168
	v_lshlrev_b32_e32 v36, 16, v169
	v_and_b32_e32 v37, 0xffff0000, v169
	v_lshlrev_b32_e32 v66, 16, v170
	v_and_b32_e32 v67, 0xffff0000, v170
	v_lshlrev_b32_e32 v68, 16, v171
	v_and_b32_e32 v69, 0xffff0000, v171
.Lpd_su3:
	s_and_b32 s64, s4, 0xfff
	s_mov_b64 s[22:23], s[4:5]
	s_branch .LBB0_430
